# bundle: early queue claims for latent units too, widened attention epilogue stores, panel-ready invalidate issued before the poll loop
# baseline (speedup 1.0000x reference)
.Lqe2:
	s_add_i32 s23, s10, 2
	s_cmp_ge_u32 s23, s19
	s_cbranch_scc1 .LBB0_1210
	s_cmp_lt_u32 s23, s18
	s_cbranch_scc0 .LBB0_1208
	s_mov_b64 s[10:11], 0xa372000
	s_mov_b64 s[12:13], 0x5d52000
	s_mov_b64 s[16:17], s[6:7]
	s_branch .LBB0_1209
.LBB0_1216:
	v_mov_b32_e32 v4, v101
	s_nop 1
	v_permlane16_swap_b32_e32 v101, v4
	v_add_f32_e32 v4, v101, v4
	v_mov_b32_e32 v5, v4
	s_nop 1
	v_permlane32_swap_b32_e32 v4, v5
	v_add_f32_e32 v4, v4, v5
	v_div_scale_f32 v5, s[6:7], v4, v4, 1.0
	v_rcp_f32_e32 v6, v5
	v_lshlrev_b32_e32 v88, 1, v97
	v_fma_f32 v7, -v5, v6, 1.0
	v_fmac_f32_e32 v6, v7, v6
	v_div_scale_f32 v7, vcc, 1.0, v4, 1.0
	v_mul_f32_e32 v8, v7, v6
	v_fma_f32 v9, -v5, v8, v7
	v_fmac_f32_e32 v8, v9, v6
	v_fma_f32 v5, -v5, v8, v7
	v_div_fmas_f32 v5, v5, v6, v8
	v_lshlrev_b64 v[6:7], 11, v[92:93]
	v_div_fixup_f32 v4, v5, v4, 1.0
	v_lshl_add_u64 v[6:7], s[48:49], 0, v[6:7]
	v_lshl_add_u64 v[6:7], v[6:7], 0, s[44:45]
	v_pk_mul_f32 v[8:9], v[68:69], v[4:5] op_sel_hi:[1,0]
	v_pk_mul_f32 v[10:11], v[70:71], v[4:5] op_sel_hi:[1,0]
	v_lshl_add_u64 v[6:7], v[6:7], 0, v[88:89]
	v_cvt_pk_bf16_f32 v44, v8, v9
	v_cvt_pk_bf16_f32 v45, v10, v11
	s_nop 0
	v_pk_mul_f32 v[8:9], v[64:65], v[4:5] op_sel_hi:[1,0]
	v_pk_mul_f32 v[10:11], v[66:67], v[4:5] op_sel_hi:[1,0]
	v_cvt_pk_bf16_f32 v46, v8, v9
	v_cvt_pk_bf16_f32 v47, v10, v11
	v_mbcnt_lo_u32_b32 v108, -1, 0
	v_mbcnt_hi_u32_b32 v108, -1, v108
	v_and_b32_e32 v108, 16, v108
	v_lshrrev_b32_e32 v108, 1, v108
	v_mul_u32_u24_e32 v108, 3, v108
	v_mov_b32_e32 v109, 0
	v_lshl_add_u64 v[110:111], v[6:7], 0, v[108:109]
	s_nop 1
	v_permlane16_swap_b32_e32 v44, v46
	v_permlane16_swap_b32_e32 v45, v47
	flat_store_dwordx4 v[110:111], v[44:47]
	v_pk_mul_f32 v[8:9], v[72:73], v[4:5] op_sel_hi:[1,0]
	v_pk_mul_f32 v[10:11], v[74:75], v[4:5] op_sel_hi:[1,0]
	v_cvt_pk_bf16_f32 v80, v8, v9
	v_cvt_pk_bf16_f32 v81, v10, v11
	s_nop 0
	v_pk_mul_f32 v[8:9], v[76:77], v[4:5] op_sel_hi:[1,0]
	v_mov_b32_e32 v5, v100
	s_nop 1
	v_permlane16_swap_b32_e32 v100, v5
	v_add_f32_e32 v5, v100, v5
	v_cvt_pk_bf16_f32 v82, v8, v9
	v_mov_b32_e32 v9, v5
	s_nop 1
	v_permlane32_swap_b32_e32 v5, v9
	v_add_f32_e32 v10, v5, v9
	v_div_scale_f32 v11, s[6:7], v10, v10, 1.0
	v_rcp_f32_e32 v12, v11
	v_pk_mul_f32 v[4:5], v[78:79], v[4:5] op_sel_hi:[1,0]
	s_nop 0
	v_cvt_pk_bf16_f32 v83, v4, v5
	v_fma_f32 v4, -v11, v12, 1.0
	v_fmac_f32_e32 v12, v4, v12
	v_div_scale_f32 v4, vcc, 1.0, v10, 1.0
	v_mul_f32_e32 v5, v4, v12
	v_lshl_add_u64 v[110:111], v[6:7], 0, v[108:109]
	s_nop 1
	v_permlane16_swap_b32_e32 v80, v82
	v_permlane16_swap_b32_e32 v81, v83
	flat_store_dwordx4 v[110:111], v[80:83] offset:64
	v_fma_f32 v6, -v11, v5, v4
	v_fmac_f32_e32 v5, v6, v12
	v_fma_f32 v4, -v11, v5, v4
	v_div_fmas_f32 v4, v4, v12, v5
	v_lshlrev_b64 v[6:7], 11, v[90:91]
	v_div_fixup_f32 v4, v4, v10, 1.0
	v_lshl_add_u64 v[6:7], s[48:49], 0, v[6:7]
	v_lshl_add_u64 v[6:7], v[6:7], 0, s[44:45]
	v_pk_mul_f32 v[8:9], v[52:53], v[4:5] op_sel_hi:[1,0]
	v_pk_mul_f32 v[10:11], v[54:55], v[4:5] op_sel_hi:[1,0]
	v_lshl_add_u64 v[6:7], v[6:7], 0, v[88:89]
	v_cvt_pk_bf16_f32 v84, v8, v9
	v_cvt_pk_bf16_f32 v85, v10, v11
	s_nop 0
	v_pk_mul_f32 v[8:9], v[48:49], v[4:5] op_sel_hi:[1,0]
	v_pk_mul_f32 v[10:11], v[50:51], v[4:5] op_sel_hi:[1,0]
	v_cvt_pk_bf16_f32 v86, v8, v9
	v_cvt_pk_bf16_f32 v87, v10, v11
	v_lshl_add_u64 v[110:111], v[6:7], 0, v[108:109]
	s_nop 1
	v_permlane16_swap_b32_e32 v84, v86
	v_permlane16_swap_b32_e32 v85, v87
	flat_store_dwordx4 v[110:111], v[84:87]
	v_pk_mul_f32 v[8:9], v[56:57], v[4:5] op_sel_hi:[1,0]
	v_pk_mul_f32 v[10:11], v[58:59], v[4:5] op_sel_hi:[1,0]
	v_cvt_pk_bf16_f32 v104, v8, v9
	v_cvt_pk_bf16_f32 v105, v10, v11
	s_nop 0
	v_pk_mul_f32 v[8:9], v[60:61], v[4:5] op_sel_hi:[1,0]
	v_pk_mul_f32 v[4:5], v[62:63], v[4:5] op_sel_hi:[1,0]
	v_cvt_pk_bf16_f32 v106, v8, v9
	v_cvt_pk_bf16_f32 v107, v4, v5
	v_lshl_add_u64 v[110:111], v[6:7], 0, v[108:109]
	s_nop 1
	v_permlane16_swap_b32_e32 v104, v106
	v_permlane16_swap_b32_e32 v105, v107
	flat_store_dwordx4 v[110:111], v[104:107] offset:64
	s_waitcnt lgkmcnt(0)
	s_barrier
	s_and_saveexec_b64 s[6:7], s[4:5]
	s_cbranch_execz .LBB0_1198
	s_cmp_eq_u32 s32, 0
	s_cbranch_scc1 .Lqf0
	s_waitcnt vmcnt(0) lgkmcnt(0)
	ds_write_b32 v178, v253
	s_mov_b32 s32, 0
	s_branch .LBB0_1198

.Lqe8:
	s_add_i32 s10, s10, 2
	s_cmp_ge_u32 s10, s19
	s_cbranch_scc1 .LBB0_2967
	s_cmp_ge_u32 s10, s18
	s_cbranch_scc0 .LBB0_2965
	s_mov_b64 s[10:11], 0x3540000
	s_mov_b64 s[12:13], 0x3140000
	s_mov_b32 s23, s20
	s_mov_b64 s[16:17], s[8:9]
	s_branch .LBB0_2966
.LBB0_2973:
	v_mov_b32_e32 v4, v101
	s_nop 1
	v_permlane16_swap_b32_e32 v101, v4
	v_add_f32_e32 v4, v101, v4
	v_mov_b32_e32 v5, v4
	s_nop 1
	v_permlane32_swap_b32_e32 v4, v5
	v_add_f32_e32 v4, v4, v5
	v_div_scale_f32 v5, s[6:7], v4, v4, 1.0
	v_rcp_f32_e32 v6, v5
	v_lshlrev_b32_e32 v88, 1, v97
	v_fma_f32 v7, -v5, v6, 1.0
	v_fmac_f32_e32 v6, v7, v6
	v_div_scale_f32 v7, vcc, 1.0, v4, 1.0
	v_mul_f32_e32 v8, v7, v6
	v_fma_f32 v9, -v5, v8, v7
	v_fmac_f32_e32 v8, v9, v6
	v_fma_f32 v5, -v5, v8, v7
	v_div_fmas_f32 v5, v5, v6, v8
	v_lshlrev_b64 v[6:7], 11, v[92:93]
	v_div_fixup_f32 v4, v5, v4, 1.0
	v_lshl_add_u64 v[6:7], s[48:49], 0, v[6:7]
	v_lshl_add_u64 v[6:7], v[6:7], 0, s[44:45]
	v_pk_mul_f32 v[8:9], v[68:69], v[4:5] op_sel_hi:[1,0]
	v_pk_mul_f32 v[10:11], v[70:71], v[4:5] op_sel_hi:[1,0]
	v_lshl_add_u64 v[6:7], v[6:7], 0, v[88:89]
	v_cvt_pk_bf16_f32 v16, v8, v9
	v_cvt_pk_bf16_f32 v17, v10, v11
	s_nop 0
	v_pk_mul_f32 v[8:9], v[64:65], v[4:5] op_sel_hi:[1,0]
	v_pk_mul_f32 v[10:11], v[66:67], v[4:5] op_sel_hi:[1,0]
	v_cvt_pk_bf16_f32 v18, v8, v9
	v_cvt_pk_bf16_f32 v19, v10, v11
	v_mbcnt_lo_u32_b32 v32, -1, 0
	v_mbcnt_hi_u32_b32 v32, -1, v32
	v_and_b32_e32 v32, 16, v32
	v_lshrrev_b32_e32 v32, 1, v32
	v_mul_u32_u24_e32 v32, 3, v32
	v_mov_b32_e32 v33, 0
	v_lshl_add_u64 v[34:35], v[6:7], 0, v[32:33]
	s_nop 1
	v_permlane16_swap_b32_e32 v16, v18
	v_permlane16_swap_b32_e32 v17, v19
	flat_store_dwordx4 v[34:35], v[16:19]
	v_pk_mul_f32 v[8:9], v[72:73], v[4:5] op_sel_hi:[1,0]
	v_pk_mul_f32 v[10:11], v[74:75], v[4:5] op_sel_hi:[1,0]
	v_cvt_pk_bf16_f32 v20, v8, v9
	v_cvt_pk_bf16_f32 v21, v10, v11
	s_nop 0
	v_pk_mul_f32 v[8:9], v[76:77], v[4:5] op_sel_hi:[1,0]
	v_mov_b32_e32 v5, v100
	s_nop 1
	v_permlane16_swap_b32_e32 v100, v5
	v_add_f32_e32 v5, v100, v5
	v_cvt_pk_bf16_f32 v22, v8, v9
	v_mov_b32_e32 v9, v5
	s_nop 1
	v_permlane32_swap_b32_e32 v5, v9
	v_add_f32_e32 v10, v5, v9
	v_div_scale_f32 v11, s[6:7], v10, v10, 1.0
	v_rcp_f32_e32 v12, v11
	v_pk_mul_f32 v[4:5], v[78:79], v[4:5] op_sel_hi:[1,0]
	s_nop 0
	v_cvt_pk_bf16_f32 v23, v4, v5
	v_fma_f32 v4, -v11, v12, 1.0
	v_fmac_f32_e32 v12, v4, v12
	v_div_scale_f32 v4, vcc, 1.0, v10, 1.0
	v_mul_f32_e32 v5, v4, v12
	v_lshl_add_u64 v[34:35], v[6:7], 0, v[32:33]
	s_nop 1
	v_permlane16_swap_b32_e32 v20, v22
	v_permlane16_swap_b32_e32 v21, v23
	flat_store_dwordx4 v[34:35], v[20:23] offset:64
	v_fma_f32 v6, -v11, v5, v4
	v_fmac_f32_e32 v5, v6, v12
	v_fma_f32 v4, -v11, v5, v4
	v_div_fmas_f32 v4, v4, v12, v5
	v_lshlrev_b64 v[6:7], 11, v[90:91]
	v_div_fixup_f32 v4, v4, v10, 1.0
	v_lshl_add_u64 v[6:7], s[48:49], 0, v[6:7]
	v_lshl_add_u64 v[6:7], v[6:7], 0, s[44:45]
	v_pk_mul_f32 v[8:9], v[52:53], v[4:5] op_sel_hi:[1,0]
	v_pk_mul_f32 v[10:11], v[54:55], v[4:5] op_sel_hi:[1,0]
	v_lshl_add_u64 v[6:7], v[6:7], 0, v[88:89]
	v_cvt_pk_bf16_f32 v24, v8, v9
	v_cvt_pk_bf16_f32 v25, v10, v11
	s_nop 0
	v_pk_mul_f32 v[8:9], v[48:49], v[4:5] op_sel_hi:[1,0]
	v_pk_mul_f32 v[10:11], v[50:51], v[4:5] op_sel_hi:[1,0]
	v_cvt_pk_bf16_f32 v26, v8, v9
	v_cvt_pk_bf16_f32 v27, v10, v11
	v_lshl_add_u64 v[34:35], v[6:7], 0, v[32:33]
	s_nop 1
	v_permlane16_swap_b32_e32 v24, v26
	v_permlane16_swap_b32_e32 v25, v27
	flat_store_dwordx4 v[34:35], v[24:27]
	v_pk_mul_f32 v[8:9], v[56:57], v[4:5] op_sel_hi:[1,0]
	v_pk_mul_f32 v[10:11], v[58:59], v[4:5] op_sel_hi:[1,0]
	v_cvt_pk_bf16_f32 v28, v8, v9
	v_cvt_pk_bf16_f32 v29, v10, v11
	s_nop 0
	v_pk_mul_f32 v[8:9], v[60:61], v[4:5] op_sel_hi:[1,0]
	v_pk_mul_f32 v[4:5], v[62:63], v[4:5] op_sel_hi:[1,0]
	v_cvt_pk_bf16_f32 v30, v8, v9
	v_cvt_pk_bf16_f32 v31, v4, v5
	v_lshl_add_u64 v[34:35], v[6:7], 0, v[32:33]
	s_nop 1
	v_permlane16_swap_b32_e32 v28, v30
	v_permlane16_swap_b32_e32 v29, v31
	flat_store_dwordx4 v[34:35], v[28:31] offset:64
	s_waitcnt lgkmcnt(0)
	s_barrier
	s_and_saveexec_b64 s[6:7], s[4:5]
	s_cbranch_execz .LBB0_2955
	s_cmp_eq_u32 s32, 0
	s_cbranch_scc1 .Lqf5
	s_waitcnt vmcnt(0) lgkmcnt(0)
	ds_write_b32 v177, v253
	s_mov_b32 s32, 0
	s_branch .LBB0_2955
